# mix sgu item GEMM: 16 weight fragments loaded up front with counted vmcnt, LDS fragments double-buffered (was 12 serialized load round trips per g)
# speedup vs baseline: 1.0496x; 1.0016x over previous
.LBB0_432:
	s_lshl_b32 s8, s14, 8
	s_mov_b32 s9, s27
	v_lshl_add_u64 v[50:51], v[72:73], 0, s[8:9]
	global_load_dwordx4 v[24:27], v[50:51], off
	global_load_dwordx4 v[28:31], v[50:51], off offset:16
	s_lshl_b32 s26, s14, 7
	s_lshl_b64 s[10:11], s[26:27], 2
	v_lshl_add_u64 v[52:53], v[74:75], 0, s[10:11]
	v_lshl_add_u64 v[54:55], v[76:77], 0, s[10:11]
	global_load_dwordx4 v[44:47], v[52:53], off
	global_load_dwordx4 v[56:59], v[54:55], off
	global_load_dwordx4 v[60:63], v[52:53], off offset:16
	global_load_dwordx4 v[64:67], v[54:55], off offset:16
	global_load_dwordx4 v[16:19], v[52:53], off offset:32
	global_load_dwordx4 v[20:23], v[54:55], off offset:32
	ds_read_b64 v[48:49], v97 offset:34816
	global_load_dwordx4 v[32:35], v[50:51], off offset:32
	global_load_dwordx4 v[36:39], v[52:53], off offset:48
	global_load_dwordx4 v[40:43], v[54:55], off offset:48
	global_load_dwordx4 v[0:3], v[52:53], off offset:80
	global_load_dwordx4 v[8:11], v[52:53], off offset:64
	global_load_dwordx4 v[4:7], v[54:55], off offset:80
	global_load_dwordx4 v[12:15], v[54:55], off offset:64
	s_lshl_b32 s26, s14, 15
	s_mov_b64 s[16:17], 0xc0
	s_movk_i32 s2, 0xffc0
	s_add_u32 s10, s12, s10
	s_addc_u32 s11, s13, s11
	s_waitcnt vmcnt(14)
	v_lshlrev_b32_e32 v68, 16, v24
	v_lshlrev_b32_e32 v69, 16, v25
	v_lshlrev_b32_e32 v70, 16, v26
	v_lshlrev_b32_e32 v71, 16, v27
	s_waitcnt vmcnt(13)
	v_lshlrev_b32_e32 v94, 16, v28
	v_and_b32_e32 v24, 0xffff0000, v24
	v_and_b32_e32 v25, 0xffff0000, v25
	v_and_b32_e32 v26, 0xffff0000, v26
	v_and_b32_e32 v27, 0xffff0000, v27
	v_and_b32_e32 v28, 0xffff0000, v28
	v_lshlrev_b32_e32 v99, 16, v31
	v_and_b32_e32 v100, 0xffff0000, v31
	s_waitcnt lgkmcnt(0)
	v_sub_f32_e32 v31, v68, v48
	v_sub_f32_e32 v68, v69, v48
	v_sub_f32_e32 v69, v70, v48
	v_sub_f32_e32 v70, v71, v48
	v_sub_f32_e32 v71, v94, v48
	v_sub_f32_e32 v24, v24, v48
	v_sub_f32_e32 v25, v25, v48
	v_sub_f32_e32 v26, v26, v48
	v_sub_f32_e32 v27, v27, v48
	v_sub_f32_e32 v28, v28, v48
	v_mul_f32_e32 v31, v49, v31
	v_mul_f32_e32 v71, v49, v71
	v_mul_f32_e32 v24, v49, v24
	v_mul_f32_e32 v68, v49, v68
	v_mul_f32_e32 v25, v49, v25
	v_mul_f32_e32 v69, v49, v69
	v_mul_f32_e32 v26, v49, v26
	v_mul_f32_e32 v70, v49, v70
	v_mul_f32_e32 v27, v49, v27
	v_mul_f32_e32 v28, v49, v28
	s_waitcnt vmcnt(11)
	v_fma_f32 v31, v44, v31, v56
	s_waitcnt vmcnt(7)
	v_fma_f32 v16, v16, v71, v20
	v_lshlrev_b32_e32 v95, 16, v29
	v_fma_f32 v24, v45, v24, v57
	v_fma_f32 v44, v68, v46, v58
	v_fmac_f32_e32 v59, v25, v47
	v_fma_f32 v25, v69, v60, v64
	v_fma_f32 v26, v26, v61, v65
	v_fma_f32 v45, v70, v62, v66
	v_fmac_f32_e32 v67, v27, v63
	v_fma_f32 v17, v17, v28, v21
	v_cvt_pk_bf16_f32 v20, v31, s0
	v_cvt_pk_bf16_f32 v16, v16, s0
	v_cvt_pk_bf16_f32 v21, v24, s0
	v_cvt_pk_bf16_f32 v24, v44, s0
	v_cvt_pk_bf16_f32 v27, v59, s0
	v_cvt_pk_bf16_f32 v25, v25, s0
	v_cvt_pk_bf16_f32 v26, v26, s0
	v_cvt_pk_bf16_f32 v28, v45, s0
	v_cvt_pk_bf16_f32 v31, v67, s0
	v_cvt_pk_bf16_f32 v17, v17, s0
	ds_write_b16 v84, v20
	ds_write_b16 v84, v21 offset:272
	ds_write_b16 v84, v24 offset:544
	ds_write_b16 v84, v27 offset:816
	ds_write_b16 v84, v25 offset:1088
	ds_write_b16 v84, v26 offset:1360
	ds_write_b16 v84, v28 offset:1632
	ds_write_b16 v84, v31 offset:1904
	ds_write_b16 v84, v16 offset:2176
	ds_write_b16 v84, v17 offset:2448
	v_sub_f32_e32 v16, v95, v48
	v_mul_f32_e32 v16, v49, v16
	v_fma_f32 v16, v16, v18, v22
	v_and_b32_e32 v29, 0xffff0000, v29
	v_cvt_pk_bf16_f32 v16, v16, s0
	ds_write_b16 v84, v16 offset:2720
	v_sub_f32_e32 v16, v29, v48
	v_mul_f32_e32 v16, v49, v16
	v_fmac_f32_e32 v23, v16, v19
	v_lshlrev_b32_e32 v98, 16, v30
	v_cvt_pk_bf16_f32 v16, v23, s0
	ds_write_b16 v84, v16 offset:2992
	v_sub_f32_e32 v16, v98, v48
	v_mul_f32_e32 v16, v49, v16
	global_load_dwordx4 v[44:47], v[50:51], off offset:48
	s_waitcnt vmcnt(5)
	v_fma_f32 v16, v16, v36, v40
	v_cvt_pk_bf16_f32 v16, v16, s0
	v_and_b32_e32 v30, 0xffff0000, v30
	ds_write_b16 v84, v16 offset:3264
	v_sub_f32_e32 v16, v30, v48
	global_load_dwordx4 v[24:27], v[52:53], off offset:96
	global_load_dwordx4 v[28:31], v[54:55], off offset:96
	v_mul_f32_e32 v16, v49, v16
	v_fma_f32 v16, v16, v37, v41
	v_cvt_pk_bf16_f32 v16, v16, s0
	ds_write_b16 v84, v16 offset:3536
	v_sub_f32_e32 v16, v99, v48
	v_mul_f32_e32 v16, v49, v16
	v_fma_f32 v16, v16, v38, v42
	v_cvt_pk_bf16_f32 v16, v16, s0
	ds_write_b16 v84, v16 offset:3808
	v_sub_f32_e32 v16, v100, v48
	v_mul_f32_e32 v16, v49, v16
	v_fmac_f32_e32 v43, v16, v39
	v_cvt_pk_bf16_f32 v16, v43, s0
	ds_write_b16 v84, v16 offset:4080
	global_load_dwordx4 v[16:19], v[52:53], off offset:112
	global_load_dwordx4 v[20:23], v[54:55], off offset:112
	v_lshlrev_b32_e32 v36, 16, v32
	v_lshlrev_b32_e32 v39, 16, v35
	v_and_b32_e32 v60, 0xffff0000, v35
	v_sub_f32_e32 v35, v36, v48
	v_mul_f32_e32 v35, v49, v35
	s_waitcnt vmcnt(5)
	v_fma_f32 v8, v8, v35, v12
	v_and_b32_e32 v32, 0xffff0000, v32
	v_cvt_pk_bf16_f32 v8, v8, s0
	ds_write_b16 v84, v8 offset:4352
	v_sub_f32_e32 v8, v32, v48
	v_mul_f32_e32 v8, v49, v8
	v_fma_f32 v8, v9, v8, v13
	v_lshlrev_b32_e32 v37, 16, v33
	v_cvt_pk_bf16_f32 v8, v8, s0
	ds_write_b16 v84, v8 offset:4624
	v_sub_f32_e32 v8, v37, v48
	v_mul_f32_e32 v8, v49, v8
	v_fma_f32 v8, v8, v10, v14
	v_and_b32_e32 v33, 0xffff0000, v33
	v_cvt_pk_bf16_f32 v8, v8, s0
	ds_write_b16 v84, v8 offset:4896
	v_sub_f32_e32 v8, v33, v48
	v_mul_f32_e32 v8, v49, v8
	v_fmac_f32_e32 v15, v8, v11
	v_lshlrev_b32_e32 v38, 16, v34
	v_cvt_pk_bf16_f32 v8, v15, s0
	ds_write_b16 v84, v8 offset:5168
	v_sub_f32_e32 v8, v38, v48
	v_mul_f32_e32 v8, v49, v8
	global_load_dwordx4 v[40:43], v[50:51], off offset:64
	v_fma_f32 v0, v8, v0, v4
	v_and_b32_e32 v34, 0xffff0000, v34
	v_cvt_pk_bf16_f32 v0, v0, s0
	ds_write_b16 v84, v0 offset:5440
	v_sub_f32_e32 v0, v34, v48
	global_load_dwordx4 v[56:59], v[52:53], off offset:128
	global_load_dwordx4 v[32:35], v[54:55], off offset:128
	v_mul_f32_e32 v0, v49, v0
	v_fma_f32 v0, v0, v1, v5
	v_cvt_pk_bf16_f32 v0, v0, s0
	ds_write_b16 v84, v0 offset:5712
	v_sub_f32_e32 v0, v39, v48
	v_mul_f32_e32 v0, v49, v0
	v_fma_f32 v0, v0, v2, v6
	v_cvt_pk_bf16_f32 v0, v0, s0
	ds_write_b16 v84, v0 offset:5984
	v_sub_f32_e32 v0, v60, v48
	v_mul_f32_e32 v0, v49, v0
	v_fmac_f32_e32 v7, v0, v3
	v_cvt_pk_bf16_f32 v0, v7, s0
	ds_write_b16 v84, v0 offset:6256
	global_load_dwordx4 v[0:3], v[52:53], off offset:144
	global_load_dwordx4 v[4:7], v[54:55], off offset:144
	global_load_dwordx4 v[36:39], v[50:51], off offset:80
	s_waitcnt vmcnt(10)
	v_lshlrev_b32_e32 v8, 16, v44
	v_sub_f32_e32 v8, v8, v48
	v_mul_f32_e32 v8, v49, v8
	v_and_b32_e32 v9, 0xffff0000, v44
	v_lshlrev_b32_e32 v10, 16, v45
	v_and_b32_e32 v11, 0xffff0000, v45
	s_waitcnt vmcnt(8)
	v_fma_f32 v8, v24, v8, v28
	v_cvt_pk_bf16_f32 v8, v8, s0
	ds_write_b16 v84, v8 offset:6528
	v_sub_f32_e32 v8, v9, v48
	v_mul_f32_e32 v8, v49, v8
	v_fma_f32 v8, v25, v8, v29
	v_cvt_pk_bf16_f32 v8, v8, s0
	ds_write_b16 v84, v8 offset:6800
	v_sub_f32_e32 v8, v10, v48
	v_mul_f32_e32 v8, v49, v8
	v_fma_f32 v8, v8, v26, v30
	v_cvt_pk_bf16_f32 v8, v8, s0
	ds_write_b16 v84, v8 offset:7072
	v_sub_f32_e32 v8, v11, v48
	v_mul_f32_e32 v8, v49, v8
	v_fmac_f32_e32 v31, v8, v27
	v_lshlrev_b32_e32 v12, 16, v46
	v_cvt_pk_bf16_f32 v8, v31, s0
	ds_write_b16 v84, v8 offset:7344
	v_sub_f32_e32 v8, v12, v48
	v_mul_f32_e32 v8, v49, v8
	s_waitcnt vmcnt(6)
	v_fma_f32 v8, v8, v16, v20
	v_cvt_pk_bf16_f32 v8, v8, s0
	v_and_b32_e32 v13, 0xffff0000, v46
	ds_write_b16 v84, v8 offset:7616
	v_sub_f32_e32 v16, v13, v48
	global_load_dwordx4 v[8:11], v[52:53], off offset:160
	global_load_dwordx4 v[12:15], v[54:55], off offset:160
	v_mul_f32_e32 v16, v49, v16
	v_fma_f32 v16, v16, v17, v21
	v_lshlrev_b32_e32 v44, 16, v47
	v_cvt_pk_bf16_f32 v16, v16, s0
	ds_write_b16 v84, v16 offset:7888
	v_sub_f32_e32 v16, v44, v48
	v_mul_f32_e32 v16, v49, v16
	v_fma_f32 v16, v16, v18, v22
	v_and_b32_e32 v45, 0xffff0000, v47
	v_cvt_pk_bf16_f32 v16, v16, s0
	ds_write_b16 v84, v16 offset:8160
	v_sub_f32_e32 v16, v45, v48
	v_mul_f32_e32 v16, v49, v16
	v_fmac_f32_e32 v23, v16, v19
	v_cvt_pk_bf16_f32 v16, v23, s0
	ds_write_b16 v84, v16 offset:8432
	global_load_dwordx4 v[16:19], v[52:53], off offset:176
	global_load_dwordx4 v[20:23], v[54:55], off offset:176
	s_waitcnt vmcnt(9)
	v_lshlrev_b32_e32 v24, 16, v40
	v_sub_f32_e32 v24, v24, v48
	v_mul_f32_e32 v24, v49, v24
	v_and_b32_e32 v25, 0xffff0000, v40
	v_lshlrev_b32_e32 v26, 16, v41
	v_and_b32_e32 v27, 0xffff0000, v41
	s_waitcnt vmcnt(7)
	v_fma_f32 v24, v56, v24, v32
	v_cvt_pk_bf16_f32 v24, v24, s0
	ds_write_b16 v84, v24 offset:8704
	v_sub_f32_e32 v24, v25, v48
	v_mul_f32_e32 v24, v49, v24
	v_fma_f32 v24, v57, v24, v33
	v_cvt_pk_bf16_f32 v24, v24, s0
	ds_write_b16 v84, v24 offset:8976
	v_sub_f32_e32 v24, v26, v48
	v_mul_f32_e32 v24, v49, v24
	v_fma_f32 v24, v24, v58, v34
	v_lshlrev_b32_e32 v28, 16, v42
	v_cvt_pk_bf16_f32 v24, v24, s0
	ds_write_b16 v84, v24 offset:9248
	v_sub_f32_e32 v24, v27, v48
	v_sub_f32_e32 v28, v28, v48
	v_mul_f32_e32 v24, v49, v24
	v_mul_f32_e32 v28, v49, v28
	v_fmac_f32_e32 v35, v24, v59
	global_load_dwordx4 v[24:27], v[50:51], off offset:96
	s_waitcnt vmcnt(6)
	v_fma_f32 v0, v28, v0, v4
	v_and_b32_e32 v29, 0xffff0000, v42
	v_cvt_pk_bf16_f32 v30, v35, s0
	v_cvt_pk_bf16_f32 v0, v0, s0
	ds_write_b16 v84, v30 offset:9520
	ds_write_b16 v84, v0 offset:9792
	v_sub_f32_e32 v0, v29, v48
	global_load_dwordx4 v[28:31], v[52:53], off offset:192
	global_load_dwordx4 v[32:35], v[54:55], off offset:192
	v_mul_f32_e32 v0, v49, v0
	v_fma_f32 v0, v0, v1, v5
	v_lshlrev_b32_e32 v40, 16, v43
	v_cvt_pk_bf16_f32 v0, v0, s0
	ds_write_b16 v84, v0 offset:10064
	v_sub_f32_e32 v0, v40, v48
	v_mul_f32_e32 v0, v49, v0
	v_fma_f32 v0, v0, v2, v6
	v_and_b32_e32 v41, 0xffff0000, v43
	v_cvt_pk_bf16_f32 v0, v0, s0
	ds_write_b16 v84, v0 offset:10336
	v_sub_f32_e32 v0, v41, v48
	v_mul_f32_e32 v0, v49, v0
	v_fmac_f32_e32 v7, v0, v3
	v_cvt_pk_bf16_f32 v0, v7, s0
	ds_write_b16 v84, v0 offset:10608
	s_waitcnt vmcnt(7)
	v_lshlrev_b32_e32 v40, 16, v36
	v_lshlrev_b32_e32 v41, 16, v37
	v_and_b32_e32 v42, 0xffff0000, v37
	global_load_dwordx4 v[0:3], v[52:53], off offset:208
	global_load_dwordx4 v[4:7], v[54:55], off offset:208
	v_sub_f32_e32 v37, v40, v48
	v_mul_f32_e32 v37, v49, v37
	v_and_b32_e32 v36, 0xffff0000, v36
	v_lshlrev_b32_e32 v43, 16, v38
	v_and_b32_e32 v44, 0xffff0000, v38
	v_lshlrev_b32_e32 v45, 16, v39
	v_and_b32_e32 v46, 0xffff0000, v39
	s_waitcnt vmcnt(7)
	v_fma_f32 v8, v8, v37, v12
	v_cvt_pk_bf16_f32 v8, v8, s0
	ds_write_b16 v84, v8 offset:10880
	v_sub_f32_e32 v8, v36, v48
	v_mul_f32_e32 v8, v49, v8
	v_fma_f32 v8, v9, v8, v13
	v_cvt_pk_bf16_f32 v8, v8, s0
	ds_write_b16 v84, v8 offset:11152
	v_sub_f32_e32 v8, v41, v48
	v_mul_f32_e32 v8, v49, v8
	v_fma_f32 v8, v8, v10, v14
	v_cvt_pk_bf16_f32 v8, v8, s0
	ds_write_b16 v84, v8 offset:11424
	v_sub_f32_e32 v8, v42, v48
	v_mul_f32_e32 v8, v49, v8
	global_load_dwordx4 v[36:39], v[50:51], off offset:112
	v_fmac_f32_e32 v15, v8, v11
	v_cvt_pk_bf16_f32 v8, v15, s0
	ds_write_b16 v84, v8 offset:11696
	global_load_dwordx4 v[8:11], v[52:53], off offset:224
	global_load_dwordx4 v[12:15], v[54:55], off offset:224
	v_sub_f32_e32 v40, v43, v48
	v_mul_f32_e32 v40, v49, v40
	s_waitcnt vmcnt(8)
	v_fma_f32 v16, v40, v16, v20
	v_cvt_pk_bf16_f32 v16, v16, s0
	ds_write_b16 v84, v16 offset:11968
	v_sub_f32_e32 v16, v44, v48
	v_mul_f32_e32 v16, v49, v16
	v_fma_f32 v16, v16, v17, v21
	v_cvt_pk_bf16_f32 v16, v16, s0
	ds_write_b16 v84, v16 offset:12240
	v_sub_f32_e32 v16, v45, v48
	v_mul_f32_e32 v16, v49, v16
	v_fma_f32 v16, v16, v18, v22
	v_cvt_pk_bf16_f32 v16, v16, s0
	ds_write_b16 v84, v16 offset:12512
	v_sub_f32_e32 v16, v46, v48
	v_mul_f32_e32 v16, v49, v16
	v_fmac_f32_e32 v23, v16, v19
	v_cvt_pk_bf16_f32 v40, v23, s0
	global_load_dwordx4 v[16:19], v[52:53], off offset:240
	global_load_dwordx4 v[20:23], v[54:55], off offset:240
	ds_write_b16 v84, v40 offset:12784
	s_waitcnt vmcnt(9)
	v_lshlrev_b32_e32 v40, 16, v24
	v_and_b32_e32 v24, 0xffff0000, v24
	v_sub_f32_e32 v24, v24, v48
	v_mul_f32_e32 v24, v49, v24
	v_lshlrev_b32_e32 v41, 16, v25
	v_and_b32_e32 v25, 0xffff0000, v25
	v_lshlrev_b32_e32 v42, 16, v26
	v_and_b32_e32 v26, 0xffff0000, v26
	s_waitcnt vmcnt(7)
	v_fma_f32 v24, v29, v24, v33
	v_cvt_pk_bf16_f32 v24, v24, s0
	ds_write_b16 v84, v24 offset:13328
	v_sub_f32_e32 v24, v41, v48
	v_mul_f32_e32 v24, v49, v24
	v_fma_f32 v24, v24, v30, v34
	v_cvt_pk_bf16_f32 v24, v24, s0
	ds_write_b16 v84, v24 offset:13600
	v_sub_f32_e32 v24, v25, v48
	v_mul_f32_e32 v24, v49, v24
	v_fmac_f32_e32 v35, v24, v31
	v_cvt_pk_bf16_f32 v24, v35, s0
	ds_write_b16 v84, v24 offset:13872
	v_sub_f32_e32 v24, v42, v48
	v_mul_f32_e32 v24, v49, v24
	v_lshlrev_b32_e32 v43, 16, v27
	v_and_b32_e32 v27, 0xffff0000, v27
	v_sub_f32_e32 v40, v40, v48
	v_mul_f32_e32 v40, v49, v40
	v_fma_f32 v28, v28, v40, v32
	s_waitcnt vmcnt(5)
	v_fma_f32 v0, v24, v0, v4
	v_cvt_pk_bf16_f32 v0, v0, s0
	ds_write_b16 v84, v0 offset:14144
	v_sub_f32_e32 v0, v26, v48
	v_mul_f32_e32 v0, v49, v0
	v_fma_f32 v0, v0, v1, v5
	v_cvt_pk_bf16_f32 v0, v0, s0
	ds_write_b16 v84, v0 offset:14416
	v_sub_f32_e32 v0, v43, v48
	v_mul_f32_e32 v0, v49, v0
	v_fma_f32 v0, v0, v2, v6
	v_cvt_pk_bf16_f32 v0, v0, s0
	ds_write_b16 v84, v0 offset:14688
	v_sub_f32_e32 v0, v27, v48
	v_mul_f32_e32 v0, v49, v0
	v_fmac_f32_e32 v7, v0, v3
	v_cvt_pk_bf16_f32 v0, v7, s0
	ds_write_b16 v84, v0 offset:14960
	v_cvt_pk_bf16_f32 v28, v28, s0
	ds_write_b16 v84, v28 offset:13056
	s_waitcnt vmcnt(4)
	v_lshlrev_b32_e32 v0, 16, v36
	v_sub_f32_e32 v0, v0, v48
	v_mul_f32_e32 v0, v49, v0
	v_and_b32_e32 v1, 0xffff0000, v36
	s_waitcnt vmcnt(2)
	v_fma_f32 v0, v8, v0, v12
	v_cvt_pk_bf16_f32 v0, v0, s0
	ds_write_b16 v84, v0 offset:15232
	v_sub_f32_e32 v0, v1, v48
	v_mul_f32_e32 v0, v49, v0
	v_fma_f32 v0, v9, v0, v13
	v_lshlrev_b32_e32 v2, 16, v37
	v_cvt_pk_bf16_f32 v0, v0, s0
	ds_write_b16 v84, v0 offset:15504
	v_sub_f32_e32 v0, v2, v48
	v_mul_f32_e32 v0, v49, v0
	v_fma_f32 v0, v0, v10, v14
	v_and_b32_e32 v3, 0xffff0000, v37
	v_cvt_pk_bf16_f32 v0, v0, s0
	ds_write_b16 v84, v0 offset:15776
	v_sub_f32_e32 v0, v3, v48
	v_mul_f32_e32 v0, v49, v0
	v_fmac_f32_e32 v15, v0, v11
	v_lshlrev_b32_e32 v4, 16, v38
	v_cvt_pk_bf16_f32 v0, v15, s0
	ds_write_b16 v84, v0 offset:16048
	v_sub_f32_e32 v0, v4, v48
	v_mul_f32_e32 v0, v49, v0
	s_waitcnt vmcnt(0)
	v_fma_f32 v0, v0, v16, v20
	v_and_b32_e32 v5, 0xffff0000, v38
	v_cvt_pk_bf16_f32 v0, v0, s0
	ds_write_b16 v84, v0 offset:16320
	v_sub_f32_e32 v0, v5, v48
	v_mul_f32_e32 v0, v49, v0
	v_fma_f32 v0, v0, v17, v21
	v_lshlrev_b32_e32 v6, 16, v39
	v_cvt_pk_bf16_f32 v0, v0, s0
	ds_write_b16 v84, v0 offset:16592
	v_sub_f32_e32 v0, v6, v48
	v_mul_f32_e32 v0, v49, v0
	v_fma_f32 v0, v0, v18, v22
	v_and_b32_e32 v7, 0xffff0000, v39
	v_cvt_pk_bf16_f32 v0, v0, s0
	ds_write_b16 v84, v0 offset:16864
	v_sub_f32_e32 v0, v7, v48
	v_mul_f32_e32 v0, v49, v0
	v_fmac_f32_e32 v23, v0, v19
	v_cvt_pk_bf16_f32 v0, v23, s0
	ds_write_b16 v81, v0
	v_lshl_add_u64 v[0:1], v[78:79], 0, s[26:27]
	v_lshl_add_u64 v[2:3], v[86:87], 1, v[0:1]
	v_lshl_add_u64 v[36:37], v[0:1], 0, v[88:89]
	v_lshl_add_u64 v[52:53], v[0:1], 0, v[90:91]
	v_lshl_add_u64 v[68:69], v[0:1], 0, v[92:93]
	s_waitcnt lgkmcnt(0)
	s_barrier
	global_load_dwordx4 v[164:167], v[2:3], off
	global_load_dwordx4 v[168:171], v[36:37], off
	global_load_dwordx4 v[172:175], v[52:53], off
	global_load_dwordx4 v[176:179], v[68:69], off
	global_load_dwordx4 v[180:183], v[2:3], off offset:64
	global_load_dwordx4 v[184:187], v[36:37], off offset:64
	global_load_dwordx4 v[188:191], v[52:53], off offset:64
	global_load_dwordx4 v[192:195], v[68:69], off offset:64
	global_load_dwordx4 v[208:211], v[2:3], off offset:128
	global_load_dwordx4 v[212:215], v[36:37], off offset:128
	global_load_dwordx4 v[216:219], v[52:53], off offset:128
	global_load_dwordx4 v[224:227], v[68:69], off offset:128
	global_load_dwordx4 v[228:231], v[2:3], off offset:192
	global_load_dwordx4 v[232:235], v[36:37], off offset:192
	global_load_dwordx4 v[236:239], v[52:53], off offset:192
	global_load_dwordx4 v[244:247], v[68:69], off offset:192
	ds_read_b128 v[98:101], v85
	ds_read_b128 v[102:105], v85 offset:4352
	ds_read_b128 v[106:109], v85 offset:8704
	ds_read_b128 v[110:113], v85 offset:13056
	ds_read_b128 v[126:129], v85 offset:64
	ds_read_b128 v[130:133], v85 offset:4416
	ds_read_b128 v[134:137], v85 offset:8768
	ds_read_b128 v[138:141], v85 offset:13120
	s_waitcnt vmcnt(15) lgkmcnt(4)
	v_mfma_f32_16x16x32_bf16 v[64:67], v[164:167], v[98:101], 0
	v_mfma_f32_16x16x32_bf16 v[48:51], v[164:167], v[102:105], 0
	v_mfma_f32_16x16x32_bf16 v[44:47], v[164:167], v[106:109], 0
	v_mfma_f32_16x16x32_bf16 v[60:63], v[164:167], v[110:113], 0
	s_waitcnt vmcnt(14)
	v_mfma_f32_16x16x32_bf16 v[56:59], v[168:171], v[98:101], 0
	v_mfma_f32_16x16x32_bf16 v[40:43], v[168:171], v[102:105], 0
	v_mfma_f32_16x16x32_bf16 v[36:39], v[168:171], v[106:109], 0
	v_mfma_f32_16x16x32_bf16 v[28:31], v[168:171], v[110:113], 0
	s_waitcnt vmcnt(13)
	v_mfma_f32_16x16x32_bf16 v[32:35], v[172:175], v[98:101], 0
	v_mfma_f32_16x16x32_bf16 v[24:27], v[172:175], v[102:105], 0
	v_mfma_f32_16x16x32_bf16 v[20:23], v[172:175], v[106:109], 0
	v_mfma_f32_16x16x32_bf16 v[12:15], v[172:175], v[110:113], 0
	s_waitcnt vmcnt(12)
	v_mfma_f32_16x16x32_bf16 v[4:7], v[176:179], v[98:101], 0
	v_mfma_f32_16x16x32_bf16 v[0:3], v[176:179], v[102:105], 0
	v_mfma_f32_16x16x32_bf16 v[8:11], v[176:179], v[106:109], 0
	v_mfma_f32_16x16x32_bf16 v[16:19], v[176:179], v[110:113], 0
	ds_read_b128 v[98:101], v85 offset:128
	ds_read_b128 v[102:105], v85 offset:4480
	ds_read_b128 v[106:109], v85 offset:8832
	ds_read_b128 v[110:113], v85 offset:13184
	s_waitcnt vmcnt(11) lgkmcnt(4)
	v_mfma_f32_16x16x32_bf16 v[64:67], v[180:183], v[126:129], v[64:67]
	v_mfma_f32_16x16x32_bf16 v[48:51], v[180:183], v[130:133], v[48:51]
	v_mfma_f32_16x16x32_bf16 v[44:47], v[180:183], v[134:137], v[44:47]
	v_mfma_f32_16x16x32_bf16 v[60:63], v[180:183], v[138:141], v[60:63]
	s_waitcnt vmcnt(10)
	v_mfma_f32_16x16x32_bf16 v[56:59], v[184:187], v[126:129], v[56:59]
	v_mfma_f32_16x16x32_bf16 v[40:43], v[184:187], v[130:133], v[40:43]
	v_mfma_f32_16x16x32_bf16 v[36:39], v[184:187], v[134:137], v[36:39]
	v_mfma_f32_16x16x32_bf16 v[28:31], v[184:187], v[138:141], v[28:31]
	s_waitcnt vmcnt(9)
	v_mfma_f32_16x16x32_bf16 v[32:35], v[188:191], v[126:129], v[32:35]
	v_mfma_f32_16x16x32_bf16 v[24:27], v[188:191], v[130:133], v[24:27]
	v_mfma_f32_16x16x32_bf16 v[20:23], v[188:191], v[134:137], v[20:23]
	v_mfma_f32_16x16x32_bf16 v[12:15], v[188:191], v[138:141], v[12:15]
	s_waitcnt vmcnt(8)
	v_mfma_f32_16x16x32_bf16 v[4:7], v[192:195], v[126:129], v[4:7]
	v_mfma_f32_16x16x32_bf16 v[0:3], v[192:195], v[130:133], v[0:3]
	v_mfma_f32_16x16x32_bf16 v[8:11], v[192:195], v[134:137], v[8:11]
	v_mfma_f32_16x16x32_bf16 v[16:19], v[192:195], v[138:141], v[16:19]
	ds_read_b128 v[126:129], v85 offset:192
	ds_read_b128 v[130:133], v85 offset:4544
	ds_read_b128 v[134:137], v85 offset:8896
	ds_read_b128 v[138:141], v85 offset:13248
	s_waitcnt vmcnt(7) lgkmcnt(4)
	v_mfma_f32_16x16x32_bf16 v[64:67], v[208:211], v[98:101], v[64:67]
	v_mfma_f32_16x16x32_bf16 v[48:51], v[208:211], v[102:105], v[48:51]
	v_mfma_f32_16x16x32_bf16 v[44:47], v[208:211], v[106:109], v[44:47]
	v_mfma_f32_16x16x32_bf16 v[60:63], v[208:211], v[110:113], v[60:63]
	s_waitcnt vmcnt(6)
	v_mfma_f32_16x16x32_bf16 v[56:59], v[212:215], v[98:101], v[56:59]
	v_mfma_f32_16x16x32_bf16 v[40:43], v[212:215], v[102:105], v[40:43]
	v_mfma_f32_16x16x32_bf16 v[36:39], v[212:215], v[106:109], v[36:39]
	v_mfma_f32_16x16x32_bf16 v[28:31], v[212:215], v[110:113], v[28:31]
	s_waitcnt vmcnt(5)
	v_mfma_f32_16x16x32_bf16 v[32:35], v[216:219], v[98:101], v[32:35]
	v_mfma_f32_16x16x32_bf16 v[24:27], v[216:219], v[102:105], v[24:27]
	v_mfma_f32_16x16x32_bf16 v[20:23], v[216:219], v[106:109], v[20:23]
	v_mfma_f32_16x16x32_bf16 v[12:15], v[216:219], v[110:113], v[12:15]
	s_waitcnt vmcnt(4)
	v_mfma_f32_16x16x32_bf16 v[4:7], v[224:227], v[98:101], v[4:7]
	v_mfma_f32_16x16x32_bf16 v[0:3], v[224:227], v[102:105], v[0:3]
	v_mfma_f32_16x16x32_bf16 v[8:11], v[224:227], v[106:109], v[8:11]
	v_mfma_f32_16x16x32_bf16 v[16:19], v[224:227], v[110:113], v[16:19]
	s_waitcnt vmcnt(3) lgkmcnt(0)
	v_mfma_f32_16x16x32_bf16 v[64:67], v[228:231], v[126:129], v[64:67]
	v_mfma_f32_16x16x32_bf16 v[48:51], v[228:231], v[130:133], v[48:51]
	v_mfma_f32_16x16x32_bf16 v[44:47], v[228:231], v[134:137], v[44:47]
	v_mfma_f32_16x16x32_bf16 v[60:63], v[228:231], v[138:141], v[60:63]
	s_waitcnt vmcnt(2)
	v_mfma_f32_16x16x32_bf16 v[56:59], v[232:235], v[126:129], v[56:59]
	v_mfma_f32_16x16x32_bf16 v[40:43], v[232:235], v[130:133], v[40:43]
	v_mfma_f32_16x16x32_bf16 v[36:39], v[232:235], v[134:137], v[36:39]
	v_mfma_f32_16x16x32_bf16 v[28:31], v[232:235], v[138:141], v[28:31]
	s_waitcnt vmcnt(1)
	v_mfma_f32_16x16x32_bf16 v[32:35], v[236:239], v[126:129], v[32:35]
	v_mfma_f32_16x16x32_bf16 v[24:27], v[236:239], v[130:133], v[24:27]
	v_mfma_f32_16x16x32_bf16 v[20:23], v[236:239], v[134:137], v[20:23]
	v_mfma_f32_16x16x32_bf16 v[12:15], v[236:239], v[138:141], v[12:15]
	s_waitcnt vmcnt(0)
	v_mfma_f32_16x16x32_bf16 v[4:7], v[244:247], v[126:129], v[4:7]
	v_mfma_f32_16x16x32_bf16 v[0:3], v[244:247], v[130:133], v[0:3]
	v_mfma_f32_16x16x32_bf16 v[8:11], v[244:247], v[134:137], v[8:11]
	v_mfma_f32_16x16x32_bf16 v[16:19], v[244:247], v[138:141], v[16:19]
	s_nop 4
	v_mov_b32_e32 v100, v254
	v_lshrrev_b32_e32 v143, 2, v100
	v_ashrrev_i32_e32 v142, 1, v100
	v_and_b32_e32 v143, 12, v143
	v_and_or_b32 v98, v142, s2, v143
	v_ashrrev_i32_e32 v99, 31, v98
	v_lshl_add_u64 v[94:95], v[98:99], 2, s[10:11]
	global_load_dwordx4 v[68:71], v[94:95], off
	global_load_dwordx4 v[52:55], v[94:95], off offset:64
	v_and_b32_e32 v99, 0x4f, v100
	v_mul_lo_u32 v98, v98, s42
	v_lshl_add_u32 v98, v99, 1, v98
	s_mov_b32 s2, 0
	s_waitcnt vmcnt(1)
	v_add_f32_e32 v44, v44, v68
	v_cvt_pk_bf16_f32 v44, v44, s0
	ds_write_b16 v98, v44 offset:35904
	v_add_f32_e32 v44, v45, v69
	v_cvt_pk_bf16_f32 v44, v44, s0
	ds_write_b16 v98, v44 offset:36176
	v_add_f32_e32 v44, v46, v70
	v_cvt_pk_bf16_f32 v44, v44, s0
	ds_write_b16 v98, v44 offset:36448
	v_add_f32_e32 v44, v47, v71
	v_cvt_pk_bf16_f32 v44, v44, s0
	ds_write_b16 v98, v44 offset:36720
	v_add_f32_e32 v44, v60, v68
	v_cvt_pk_bf16_f32 v44, v44, s0
	ds_write_b16 v98, v44 offset:35936
	v_add_f32_e32 v44, v61, v69
	v_cvt_pk_bf16_f32 v44, v44, s0
	ds_write_b16 v98, v44 offset:36208
	v_add_f32_e32 v44, v62, v70
	v_cvt_pk_bf16_f32 v44, v44, s0
	ds_write_b16 v98, v44 offset:36480
	v_add_f32_e32 v44, v63, v71
	v_cvt_pk_bf16_f32 v44, v44, s0
	v_add_f32_e32 v64, v64, v68
	ds_write_b16 v98, v44 offset:36752
	s_waitcnt vmcnt(0)
	v_add_f32_e32 v44, v56, v52
	v_cvt_pk_bf16_f32 v64, v64, s0
	v_cvt_pk_bf16_f32 v44, v44, s0
	ds_write_b16 v98, v64 offset:35840
	v_add_f32_e32 v64, v65, v69
	ds_write_b16 v98, v44 offset:40192
	v_add_f32_e32 v44, v57, v53
	v_cvt_pk_bf16_f32 v64, v64, s0
	v_cvt_pk_bf16_f32 v44, v44, s0
	ds_write_b16 v98, v64 offset:36112
	v_add_f32_e32 v64, v66, v70
	ds_write_b16 v98, v44 offset:40464
	v_add_f32_e32 v44, v58, v54
	v_cvt_pk_bf16_f32 v64, v64, s0
	v_cvt_pk_bf16_f32 v44, v44, s0
	ds_write_b16 v98, v64 offset:36384
	v_add_f32_e32 v64, v67, v71
	ds_write_b16 v98, v44 offset:40736
	v_add_f32_e32 v44, v59, v55
	v_cvt_pk_bf16_f32 v64, v64, s0
	v_cvt_pk_bf16_f32 v44, v44, s0
	ds_write_b16 v98, v64 offset:36656
	global_load_dwordx4 v[64:67], v[94:95], off offset:128
	ds_write_b16 v98, v44 offset:41008
	global_load_dwordx4 v[44:47], v[94:95], off offset:192
	v_add_f32_e32 v28, v28, v52
	v_cvt_pk_bf16_f32 v28, v28, s0
	ds_write_b16 v98, v28 offset:40288
	v_add_f32_e32 v28, v29, v53
	v_cvt_pk_bf16_f32 v28, v28, s0
	ds_write_b16 v98, v28 offset:40560
	v_add_f32_e32 v28, v30, v54
	v_cvt_pk_bf16_f32 v28, v28, s0
	ds_write_b16 v98, v28 offset:40832
	v_add_f32_e32 v28, v31, v55
	v_cvt_pk_bf16_f32 v28, v28, s0
	v_add_f32_e32 v48, v48, v68
	v_add_f32_e32 v40, v40, v52
	v_add_f32_e32 v36, v36, v52
	ds_write_b16 v98, v28 offset:41104
	v_cvt_pk_bf16_f32 v48, v48, s0
	v_cvt_pk_bf16_f32 v40, v40, s0
	v_cvt_pk_bf16_f32 v36, v36, s0
	ds_write_b16 v98, v48 offset:35872
	v_add_f32_e32 v48, v49, v69
	ds_write_b16 v98, v40 offset:40224
	v_add_f32_e32 v40, v41, v53
	ds_write_b16 v98, v36 offset:40256
	v_add_f32_e32 v36, v37, v53
	v_cvt_pk_bf16_f32 v48, v48, s0
	v_cvt_pk_bf16_f32 v40, v40, s0
	v_cvt_pk_bf16_f32 v36, v36, s0
	ds_write_b16 v98, v48 offset:36144
	v_add_f32_e32 v48, v50, v70
	ds_write_b16 v98, v40 offset:40496
	v_add_f32_e32 v40, v42, v54
	ds_write_b16 v98, v36 offset:40528
	v_add_f32_e32 v36, v38, v54
	v_cvt_pk_bf16_f32 v48, v48, s0
	v_cvt_pk_bf16_f32 v40, v40, s0
	v_cvt_pk_bf16_f32 v36, v36, s0
	ds_write_b16 v98, v48 offset:36416
	v_add_f32_e32 v48, v51, v71
	ds_write_b16 v98, v40 offset:40768
	v_add_f32_e32 v40, v43, v55
	ds_write_b16 v98, v36 offset:40800
	v_add_f32_e32 v36, v39, v55
	v_cvt_pk_bf16_f32 v48, v48, s0
	v_cvt_pk_bf16_f32 v40, v40, s0
	v_cvt_pk_bf16_f32 v36, v36, s0
	ds_write_b16 v98, v48 offset:36688
	ds_write_b16 v98, v40 offset:41040
	ds_write_b16 v98, v36 offset:41072
	s_waitcnt vmcnt(1)
	v_add_f32_e32 v28, v32, v64
	v_add_f32_e32 v24, v24, v64
	s_waitcnt vmcnt(0)
	v_add_f32_e32 v0, v0, v44
	v_cvt_pk_bf16_f32 v0, v0, s0
	ds_write_b16 v98, v0 offset:48928
	v_add_f32_e32 v0, v1, v45
	v_cvt_pk_bf16_f32 v0, v0, s0
	ds_write_b16 v98, v0 offset:49200
	v_add_f32_e32 v0, v2, v46
	v_cvt_pk_bf16_f32 v0, v0, s0
	ds_write_b16 v98, v0 offset:49472
	v_add_f32_e32 v0, v3, v47
	v_cvt_pk_bf16_f32 v0, v0, s0
	ds_write_b16 v98, v0 offset:49744
	v_add_f32_e32 v0, v8, v44
	v_cvt_pk_bf16_f32 v0, v0, s0
	ds_write_b16 v98, v0 offset:48960
	v_add_f32_e32 v0, v9, v45
	v_cvt_pk_bf16_f32 v0, v0, s0
	ds_write_b16 v98, v0 offset:49232
	v_add_f32_e32 v0, v10, v46
	v_cvt_pk_bf16_f32 v0, v0, s0
	ds_write_b16 v98, v0 offset:49504
	v_add_f32_e32 v0, v11, v47
	v_cvt_pk_bf16_f32 v0, v0, s0
	ds_write_b16 v98, v0 offset:49776
	v_add_f32_e32 v0, v16, v44
	v_add_f32_e32 v20, v20, v64
	v_add_f32_e32 v12, v12, v64
	v_add_f32_e32 v4, v4, v44
	v_cvt_pk_bf16_f32 v0, v0, s0
	v_cvt_pk_bf16_f32 v28, v28, s0
	v_cvt_pk_bf16_f32 v24, v24, s0
	v_cvt_pk_bf16_f32 v20, v20, s0
	v_cvt_pk_bf16_f32 v12, v12, s0
	v_cvt_pk_bf16_f32 v4, v4, s0
	ds_write_b16 v98, v0 offset:48992
	v_add_f32_e32 v0, v17, v45
	ds_write_b16 v98, v28 offset:44544
	v_add_f32_e32 v28, v33, v65
	ds_write_b16 v98, v24 offset:44576
	v_add_f32_e32 v24, v25, v65
	ds_write_b16 v98, v20 offset:44608
	v_add_f32_e32 v20, v21, v65
	ds_write_b16 v98, v12 offset:44640
	v_add_f32_e32 v12, v13, v65
	ds_write_b16 v98, v4 offset:48896
	v_add_f32_e32 v4, v5, v45
	v_cvt_pk_bf16_f32 v0, v0, s0
	v_cvt_pk_bf16_f32 v28, v28, s0
	v_cvt_pk_bf16_f32 v24, v24, s0
	v_cvt_pk_bf16_f32 v20, v20, s0
	v_cvt_pk_bf16_f32 v12, v12, s0
	v_cvt_pk_bf16_f32 v4, v4, s0
	ds_write_b16 v98, v0 offset:49264
	v_add_f32_e32 v0, v18, v46
	ds_write_b16 v98, v28 offset:44816
	v_add_f32_e32 v28, v34, v66
	ds_write_b16 v98, v24 offset:44848
	v_add_f32_e32 v24, v26, v66
	ds_write_b16 v98, v20 offset:44880
	v_add_f32_e32 v20, v22, v66
	ds_write_b16 v98, v12 offset:44912
	v_add_f32_e32 v12, v14, v66
	ds_write_b16 v98, v4 offset:49168
	v_add_f32_e32 v4, v6, v46
	v_cvt_pk_bf16_f32 v0, v0, s0
	v_cvt_pk_bf16_f32 v28, v28, s0
	v_cvt_pk_bf16_f32 v24, v24, s0
	v_cvt_pk_bf16_f32 v20, v20, s0
	v_cvt_pk_bf16_f32 v12, v12, s0
	v_cvt_pk_bf16_f32 v4, v4, s0
	ds_write_b16 v98, v0 offset:49536
	v_add_f32_e32 v0, v19, v47
	ds_write_b16 v98, v28 offset:45088
	v_add_f32_e32 v28, v35, v67
	ds_write_b16 v98, v24 offset:45120
	v_add_f32_e32 v24, v27, v67
	ds_write_b16 v98, v20 offset:45152
	v_add_f32_e32 v20, v23, v67
	ds_write_b16 v98, v12 offset:45184
	v_add_f32_e32 v12, v15, v67
	ds_write_b16 v98, v4 offset:49440
	v_add_f32_e32 v4, v7, v47
	v_cvt_pk_bf16_f32 v0, v0, s0
	v_cvt_pk_bf16_f32 v28, v28, s0
	v_cvt_pk_bf16_f32 v24, v24, s0
	v_cvt_pk_bf16_f32 v20, v20, s0
	v_cvt_pk_bf16_f32 v12, v12, s0
	v_cvt_pk_bf16_f32 v4, v4, s0
	ds_write_b16 v98, v0 offset:49808
	v_lshl_add_u64 v[0:1], v[82:83], 0, s[8:9]
	ds_write_b16 v98, v28 offset:45360
	ds_write_b16 v98, v24 offset:45392
	ds_write_b16 v98, v20 offset:45424
	ds_write_b16 v98, v12 offset:45456
	ds_write_b16 v98, v4 offset:49712
	s_waitcnt lgkmcnt(0)
	s_barrier
